# retention: K-fragment LDS addresses kept in registers across tiles (toggled by xor 0x8000), no address VALU before the first S-phase reads
# baseline (speedup 1.0000x reference)
; #define LAS __attribute__((address_space(3)))
; #define RT_BAR() do { asm volatile("s_waitcnt lgkmcnt(0)" ::: "memory"); __builtin_amdgcn_s_barrier(); asm volatile("" ::: "memory"); } while (0)
; __device__ __forceinline__ void p2_ret(const Frame& F, ArgsP a, int layer) {
;     ...
;             const int qi = uu ? p : 15 - p, ntile = 2 * (qi + 1);
;             const size_t tokq = (size_t)b * SEQ + qi * 128;
;             f32x16 oacc[4];
; #pragma unroll
;             for (int db = 0; db < 4; ++db)
; #pragma unroll
;                 for (int r = 0; r < 16; ++r) oacc[db][r] = 0.f;
;             asm volatile("s_waitcnt vmcnt(0)" ::: "memory"); RT_BAR();
;             for (int kt = 0; kt < ntile; ++kt) {
;                 const bool cv = cvhi < CV_HALF_ITEMS && ((cvtile++ & 1) == 0); f32x4 cvv[8], cvsc[2];
;                 if (cv) { const CvU cu = cv_decode(a, F.ws, cvhi, layer); cv_load(cu, lane, cvv, cvsc); }
;                 const int bf = kt & 1; const bool pre = kt + 1 < ntile;
;                 int lo_ = lane; asm volatile("" : "+v"(lo_));
;                 const int l31 = lo_ & 31, hh = lo_ >> 5, lane = lo_;
;                 const int kap = (l31 & 0x13) | ((l31 & 4) << 1) | ((l31 & 8) >> 1), x15 = kap & 15, m4 = ((kap >> 1) & 7) << 4;
;                 f32x16 st;
; #pragma unroll
;                 for (int r = 0; r < 16; ++r) st[r] = 0.f;
;                 { const LAS unsigned char* kb = lds + RT_K0 + bf * 32768 + (32 * wc + kap) * 512;
.LBB0_355:
	s_xor_b64 s[72:73], s[74:75], -1
	s_and_b64 s[2:3], s[74:75], exec
	s_waitcnt vmcnt(0)
	s_cselect_b32 s96, s89, s50
	s_waitcnt lgkmcnt(0)
	s_barrier
	v_lshlrev_b32_e32 v228, 1, v207
	v_lshrrev_b32_e32 v229, 1, v207
	v_and_b32_e32 v115, 19, v207
	v_and_b32_e32 v228, 8, v228
	v_and_b32_e32 v229, 4, v229
	v_or3_b32 v115, v228, v115, v229
	v_ashrrev_i32_e32 v116, 5, v207
	v_or_b32_e32 v227, s80, v115
	v_lshlrev_b32_e32 v227, 9, v227
	v_bitop3_b32 v228, v115, v116, 15 bitop3:0x6c
	v_lshl_add_u32 v228, v228, 4, v227
	v_or_b32_e32 v229, 2, v116
	v_bitop3_b32 v229, v115, v229, 15 bitop3:0x6c
	v_lshl_add_u32 v229, v229, 4, v227
	v_or_b32_e32 v230, 4, v116
	v_bitop3_b32 v230, v115, v230, 15 bitop3:0x6c
	v_lshl_add_u32 v230, v230, 4, v227
	v_or_b32_e32 v231, 6, v116
	v_bitop3_b32 v231, v115, v231, 15 bitop3:0x6c
	v_lshl_add_u32 v231, v231, 4, v227
	v_or_b32_e32 v250, 8, v116
	v_bitop3_b32 v250, v115, v250, 15 bitop3:0x6c
	v_lshl_add_u32 v250, v250, 4, v227
	v_or_b32_e32 v251, 10, v116
	v_bitop3_b32 v251, v115, v251, 15 bitop3:0x6c
	v_lshl_add_u32 v251, v251, 4, v227
	v_or_b32_e32 v252, 12, v116
	v_bitop3_b32 v252, v115, v252, 15 bitop3:0x6c
	v_lshl_add_u32 v252, v252, 4, v227
	v_or_b32_e32 v253, 14, v116
	v_bitop3_b32 v253, v115, v253, 15 bitop3:0x6c
	v_lshl_add_u32 v253, v253, 4, v227
	s_lshl_b32 s19, s96, 7
	s_lshl_b32 s11, s96, 8
	v_mov_b32_e32 v34, 0
	s_lshl_b32 s29, s96, 1
	s_add_i32 s97, s81, s19
	s_bitset1_b32 s11, 7
	s_mov_b32 s31, 0
	s_mov_b32 s27, s88
	s_mov_b32 s30, 0
	s_mov_b32 s91, 0
	v_mov_b32_e32 v35, v34
	v_mov_b32_e32 v36, v34
	v_mov_b32_e32 v37, v34
	v_mov_b32_e32 v38, v34
	v_mov_b32_e32 v39, v34
	v_mov_b32_e32 v40, v34
	v_mov_b32_e32 v41, v34
	v_mov_b32_e32 v42, v34
	v_mov_b32_e32 v43, v34
	v_mov_b32_e32 v44, v34
	v_mov_b32_e32 v45, v34
	v_mov_b32_e32 v46, v34
	v_mov_b32_e32 v47, v34
	v_mov_b32_e32 v48, v34
	v_mov_b32_e32 v49, v34
	v_mov_b32_e32 v50, v34
	v_mov_b32_e32 v51, v34
	v_mov_b32_e32 v52, v34
	v_mov_b32_e32 v53, v34
	v_mov_b32_e32 v54, v34
	v_mov_b32_e32 v55, v34
	v_mov_b32_e32 v56, v34
	v_mov_b32_e32 v57, v34
	v_mov_b32_e32 v58, v34
	v_mov_b32_e32 v59, v34
	v_mov_b32_e32 v60, v34
	v_mov_b32_e32 v61, v34
	v_mov_b32_e32 v62, v34
	v_mov_b32_e32 v63, v34
	v_mov_b32_e32 v64, v34
	v_mov_b32_e32 v65, v34
	v_mov_b32_e32 v66, v34
	v_mov_b32_e32 v67, v34
	v_mov_b32_e32 v68, v34
	v_mov_b32_e32 v69, v34
	v_mov_b32_e32 v70, v34
	v_mov_b32_e32 v71, v34
	v_mov_b32_e32 v72, v34
	v_mov_b32_e32 v73, v34
	v_mov_b32_e32 v74, v34
	v_mov_b32_e32 v75, v34
	v_mov_b32_e32 v76, v34
	v_mov_b32_e32 v77, v34
	v_mov_b32_e32 v78, v34
	v_mov_b32_e32 v79, v34
	v_mov_b32_e32 v80, v34
	v_mov_b32_e32 v81, v34
	v_mov_b32_e32 v82, v34
	v_mov_b32_e32 v83, v34
	v_mov_b32_e32 v84, v34
	v_mov_b32_e32 v85, v34
	v_mov_b32_e32 v86, v34
	v_mov_b32_e32 v87, v34
	v_mov_b32_e32 v88, v34
	v_mov_b32_e32 v89, v34
	v_mov_b32_e32 v90, v34
	v_mov_b32_e32 v91, v34
	v_mov_b32_e32 v92, v34
	v_mov_b32_e32 v93, v34
	v_mov_b32_e32 v94, v34
	v_mov_b32_e32 v95, v34
	v_mov_b32_e32 v96, v34
	v_mov_b32_e32 v97, v34
	s_branch .LBB0_358

; __device__ __forceinline__ void cv_load(const CvU& u, int lane, f32x4 (&v)[8], f32x4 (&sc)[2]) {
;     ...
;     else { sc[0] = (f32x4){1.f, 1.f, 1.f, 1.f}; sc[1] = sc[0]; }
; __device__ __forceinline__ void p2_ret(const Frame& F, ArgsP a, int layer) {
;     ...
;                 { const LAS unsigned char* kb = lds + RT_K0 + bf * 32768 + (32 * wc + kap) * 512;
;     ...
;                   bf16x8 ka[2], kd[2], kc[2];
;                   RT_KRD(ka, 0); RT_KRD(kd, 2); __builtin_amdgcn_sched_barrier(0);
;                   RT_KRD(kc, 4); RT_KMM(ka, 0); if (pre) { RT_DMA_K(kt + 1, bf ^ 1, 0); RT_DMA_V(kt + 1, bf ^ 1, 0); } __builtin_amdgcn_sched_barrier(0);
;                   RT_KRD(ka, 6); RT_KMM(kd, 2); __builtin_amdgcn_sched_barrier(0);
;                   RT_KRD(kd, 8); RT_KMM(kc, 4); if (pre) { RT_DMA_K(kt + 1, bf ^ 1, 1); RT_DMA_V(kt + 1, bf ^ 1, 1); } __builtin_amdgcn_sched_barrier(0);
;                   RT_KRD(kc, 10); RT_KMM(ka, 6); __builtin_amdgcn_sched_barrier(0);
;                   RT_KRD(ka, 12); RT_KMM(kd, 8); if (pre) { RT_DMA_K(kt + 1, bf ^ 1, 2); RT_DMA_V(kt + 1, bf ^ 1, 2); } __builtin_amdgcn_sched_barrier(0);
;                   RT_KRD(kd, 14); RT_KMM(kc, 10); __builtin_amdgcn_sched_barrier(0);
;                   RT_KMM(ka, 12); if (pre) { RT_DMA_K(kt + 1, bf ^ 1, 3); RT_DMA_V(kt + 1, bf ^ 1, 3); } __builtin_amdgcn_sched_barrier(0);
;                   RT_KMM(kd, 14); __builtin_amdgcn_sched_barrier(0);
;     ...
;                 }
;                 { const bool diag = kt >= 2 * qi;
;                   unsigned pk[8];
;                   if (!diag) { const float tf = __builtin_amdgcn_exp2f((float)(128 * (qi - (kt >> 1))) * lg2);
; #pragma unroll
;                       for (int i = 0; i < 8; ++i) pk[i] = cvt_pk_bf16(st[2 * i] * tf, st[2 * i + 1] * tf);
;                   } else { const int lim = wr * 32 + l31 + (2 * qi - kt) * 64 - 32 * wc - 8 * hh;
; #pragma unroll
;                       for (int i = 0; i < 8; ++i) { const int r0 = 2 * i, r1 = 2 * i + 1, o0 = 16 * (r0 >> 3) + (r0 & 7), o1 = 16 * (r1 >> 3) + (r1 & 7);
;                           pk[i] = cvt_pk_bf16((o0 <= lim) ? st[r0] : 0.f, (o1 <= lim) ? st[r1] : 0.f); } }
;                   LAS unsigned char* pw = lds + RT_P + ((wr * 2 + wc) * 2) * 1024 + lane * 16;
;                   *(LAS u32x4*)pw = (u32x4){pk[0], pk[1], pk[2], pk[3]}; *(LAS u32x4*)(pw + 1024) = (u32x4){pk[4], pk[5], pk[6], pk[7]}; }
.LBB0_382:
	v_mov_b32_e32 v182, v114
	v_mov_b32_e32 v183, v114
	v_mov_b32_e32 v184, v114
	v_mov_b32_e32 v185, v114
	v_mov_b32_e32 v186, v114
	v_mov_b32_e32 v187, v114
	v_mov_b32_e32 v188, v114
	v_mov_b32_e32 v189, v114
.LBB0_383:
	v_mov_b32_e32 v0, v207
	s_and_b32 s6, s31, 0x8000
	ds_read_b128 v[98:101], v228
	ds_read_b128 v[190:193], v229
	ds_read_b128 v[194:197], v230
	ds_read_b128 v[198:201], v231
	ds_read_b128 v[202:205], v250
	ds_read_b128 v[212:215], v251
	v_and_b32_e32 v117, 31, v0
	s_xor_b32 s4, s6, 0x8000
	s_add_i32 s5, s22, s4
	s_add_i32 s7, s25, s30
	s_add_i32 m0, s33, s4
	s_add_i32 s12, s7, 0x80
	s_mov_b32 s46, s42
	s_mov_b32 s47, s43
	buffer_load_dwordx4 v225, s[44:47], s12 offen lds
	s_waitcnt lgkmcnt(5)
	v_mfma_f32_32x32x16_bf16 v[98:113], v[98:101], v[118:121], 0
	s_waitcnt lgkmcnt(4)
	v_mfma_f32_32x32x16_bf16 v[98:113], v[190:193], v[122:125], v[98:113]
	ds_read_b128 v[190:193], v252
	ds_read_b128 v[216:219], v253
	s_waitcnt lgkmcnt(5)
	v_mfma_f32_32x32x16_bf16 v[98:113], v[194:197], v[126:129], v[98:113]
	s_add_i32 s4, s4, 0
	s_waitcnt lgkmcnt(4)
	v_mfma_f32_32x32x16_bf16 v[98:113], v[198:201], v[130:133], v[98:113]
	s_add_i32 s12, s27, 0xfffe0000
	s_add_i32 s4, s4, 0x10000
	ds_read_b128 v[194:197], v228 offset:256
	ds_read_b128 v[198:201], v229 offset:256
	s_add_i32 m0, s4, s24
	s_add_i32 s12, s7, 0x100080
	buffer_load_dwordx4 v225, s[44:47], s12 offen lds
	s_waitcnt lgkmcnt(5)
	v_mfma_f32_32x32x16_bf16 v[98:113], v[202:205], v[134:137], v[98:113]
	s_waitcnt lgkmcnt(4)
	v_mfma_f32_32x32x16_bf16 v[98:113], v[212:215], v[138:141], v[98:113]
	ds_read_b128 v[202:205], v230 offset:256
	ds_read_b128 v[212:215], v231 offset:256
	s_waitcnt lgkmcnt(5)
	v_mfma_f32_32x32x16_bf16 v[98:113], v[190:193], v[142:145], v[98:113]
	s_add_i32 s12, s27, 0xffff0000
	s_waitcnt lgkmcnt(4)
	v_mfma_f32_32x32x16_bf16 v[98:113], v[216:219], v[146:149], v[98:113]
	ds_read_b128 v[190:193], v250 offset:256
	ds_read_b128 v[216:219], v251 offset:256
	s_add_i32 m0, s4, s26
	s_add_i32 s12, s7, 0x200080
	buffer_load_dwordx4 v225, s[44:47], s12 offen lds
	s_waitcnt lgkmcnt(5)
	v_mfma_f32_32x32x16_bf16 v[98:113], v[194:197], v[150:153], v[98:113]
	s_waitcnt lgkmcnt(4)
	v_mfma_f32_32x32x16_bf16 v[98:113], v[198:201], v[154:157], v[98:113]
	s_waitcnt lgkmcnt(3)
	v_mfma_f32_32x32x16_bf16 v[98:113], v[202:205], v[158:161], v[98:113]
	ds_read_b128 v[194:197], v252 offset:256
	ds_read_b128 v[198:201], v253 offset:256
	s_waitcnt lgkmcnt(4)
	v_mfma_f32_32x32x16_bf16 v[98:113], v[212:215], v[162:165], v[98:113]
	s_add_i32 s7, s7, 0x300080
	s_add_i32 m0, s4, s28
	s_waitcnt lgkmcnt(3)
	v_mfma_f32_32x32x16_bf16 v[98:113], v[190:193], v[166:169], v[98:113]
	buffer_load_dwordx4 v225, s[44:47], s7 offen lds
	s_waitcnt lgkmcnt(2)
	v_mfma_f32_32x32x16_bf16 v[98:113], v[216:219], v[170:173], v[98:113]
	s_waitcnt lgkmcnt(1)
	v_mfma_f32_32x32x16_bf16 v[98:113], v[194:197], v[174:177], v[98:113]
	s_waitcnt lgkmcnt(0)
	v_mfma_f32_32x32x16_bf16 v[98:113], v[198:201], v[178:181], v[98:113]
	v_xor_b32_e32 v228, 0x8000, v228
	v_xor_b32_e32 v229, 0x8000, v229
	v_xor_b32_e32 v230, 0x8000, v230
	v_xor_b32_e32 v231, 0x8000, v231
	v_xor_b32_e32 v250, 0x8000, v250
	v_xor_b32_e32 v251, 0x8000, v251
	v_xor_b32_e32 v252, 0x8000, v252
	v_xor_b32_e32 v253, 0x8000, v253
	v_lshlrev_b32_e32 v202, 3, v115
	v_and_b32_e32 v202, 0x70, v202
	s_add_i32 s13, s64, s6
	v_lshl_add_u32 v203, v115, 7, s13
	v_lshlrev_b32_e32 v204, 4, v116
	s_lshl_b32 s14, s80, 1
	v_xad_u32 v246, v202, v204, v203
	v_add_u32_e32 v205, 32, v204
	v_xad_u32 v247, v202, v205, v203
	v_xor_b32_e32 v246, s14, v246
	v_xor_b32_e32 v247, s14, v247
	v_xor_b32_e32 v248, 64, v246
	v_xor_b32_e32 v249, 64, v247
	ds_read_b128 v[234:237], v246
	ds_read_b128 v[238:241], v247
	s_cmp_ge_u32 s91, s29
	s_mov_b64 s[4:5], -1
	s_cbranch_scc0 .LBB0_385
	v_lshlrev_b32_e32 v190, 3, v116
	v_sub_u32_e32 v117, v117, v190
	v_add_u32_e32 v117, s97, v117
	v_cmp_lt_i32_e32 vcc, -1, v117
	s_mov_b64 s[4:5], 0
	s_nop 3
	v_cndmask_b32_e32 v190, 0, v98, vcc
	v_cmp_lt_i32_e32 vcc, 0, v117
	s_nop 1
	v_cndmask_b32_e32 v191, 0, v99, vcc
	v_cmp_lt_i32_e32 vcc, 1, v117
	v_cvt_pk_bf16_f32 v190, v190, v191
	s_nop 1
	v_cndmask_b32_e32 v191, 0, v100, vcc
	v_cmp_lt_i32_e32 vcc, 2, v117
	s_nop 1
	v_cndmask_b32_e32 v192, 0, v101, vcc
	v_cmp_lt_i32_e32 vcc, 3, v117
	v_cvt_pk_bf16_f32 v191, v191, v192
	s_nop 1
	v_cndmask_b32_e32 v192, 0, v102, vcc
	v_cmp_lt_i32_e32 vcc, 4, v117
	s_nop 1
	v_cndmask_b32_e32 v193, 0, v103, vcc
	v_cmp_lt_i32_e32 vcc, 5, v117
	v_cvt_pk_bf16_f32 v192, v192, v193
	s_nop 1
	v_cndmask_b32_e32 v193, 0, v104, vcc
	v_cmp_lt_i32_e32 vcc, 6, v117
	s_nop 1
	v_cndmask_b32_e32 v194, 0, v105, vcc
	v_cmp_lt_i32_e32 vcc, 15, v117
	v_cvt_pk_bf16_f32 v193, v193, v194
	s_nop 1
	v_cndmask_b32_e32 v194, 0, v106, vcc
	v_cmp_lt_i32_e32 vcc, 16, v117
	s_nop 1
	v_cndmask_b32_e32 v195, 0, v107, vcc
	v_cmp_lt_i32_e32 vcc, 17, v117
	v_cvt_pk_bf16_f32 v194, v194, v195
	s_nop 1
	v_cndmask_b32_e32 v195, 0, v108, vcc
	v_cmp_lt_i32_e32 vcc, 18, v117
	s_nop 1
	v_cndmask_b32_e32 v196, 0, v109, vcc
	v_cmp_lt_i32_e32 vcc, 19, v117
	v_cvt_pk_bf16_f32 v195, v195, v196
	s_nop 1
	v_cndmask_b32_e32 v196, 0, v110, vcc
	v_cmp_lt_i32_e32 vcc, 20, v117
	s_nop 1
	v_cndmask_b32_e32 v197, 0, v111, vcc
	v_cmp_lt_i32_e32 vcc, 21, v117
	v_cvt_pk_bf16_f32 v196, v196, v197
	s_nop 1
	v_cndmask_b32_e32 v197, 0, v112, vcc
	v_cmp_lt_i32_e32 vcc, 22, v117
	s_nop 1
	v_cndmask_b32_e32 v117, 0, v113, vcc
	v_cvt_pk_bf16_f32 v197, v197, v117

; #define LAS __attribute__((address_space(3)))
; #define RT_BAR() do { asm volatile("s_waitcnt lgkmcnt(0)" ::: "memory"); __builtin_amdgcn_s_barrier(); asm volatile("" ::: "memory"); } while (0)
; #define RT_VRD(dst, g) do { _Pragma("unroll") for (int j_ = 0; j_ < 2; ++j_) { const int jj_ = 2 * ((g) & 1) + j_; dst[j_] = *(const LAS bf16x8*)(vb + ((g) >> 1) * 4096 + (((4 * (jj_ >> 1) + 2 * (jj_ & 1) + hh) << 4) ^ m4)); } } while (0)
; #define RT_VMM(src, g) do { _Pragma("unroll") for (int j_ = 0; j_ < 2; ++j_) { const int jj_ = 2 * ((g) & 1) + j_; oacc[(g) >> 1] = __builtin_amdgcn_mfma_f32_32x32x16_bf16(src[j_], pf[jj_ >> 1][jj_ & 1], oacc[(g) >> 1], 0, 0, 0); } } while (0)
; __device__ __forceinline__ void p2_ret(const Frame& F, ArgsP a, int layer) {
;     ...
;                   LAS unsigned char* pw = lds + RT_P + ((wr * 2 + wc) * 2) * 1024 + lane * 16;
;                   *(LAS u32x4*)pw = (u32x4){pk[0], pk[1], pk[2], pk[3]}; *(LAS u32x4*)(pw + 1024) = (u32x4){pk[4], pk[5], pk[6], pk[7]}; }
;                 RT_BAR();
;                 { bf16x8 pf[2][2];
; #pragma unroll
;                   for (int kb2 = 0; kb2 < 2; ++kb2)
; #pragma unroll
;                       for (int s = 0; s < 2; ++s) pf[kb2][s] = *(const LAS bf16x8*)(lds + RT_P + ((wr * 2 + kb2) * 2 + s) * 1024 + lane * 16);
;                   const LAS unsigned char* vb = lds + RT_V0 + bf * 32768 + (128 * wc + kap) * 128;
;     ...
;                   bf16x8 va[2], vc[2];
;                   RT_VRD(va, 0); __builtin_amdgcn_sched_barrier(0);
;                   RT_VRD(vc, 1); RT_VMM(va, 0); __builtin_amdgcn_sched_barrier(0);
;                   RT_VRD(va, 2); RT_VMM(vc, 1); __builtin_amdgcn_sched_barrier(0);
;                   RT_VRD(vc, 3); RT_VMM(va, 2); __builtin_amdgcn_sched_barrier(0);
;                   RT_VRD(va, 4); RT_VMM(vc, 3); __builtin_amdgcn_sched_barrier(0);
;                   RT_VRD(vc, 5); RT_VMM(va, 4); __builtin_amdgcn_sched_barrier(0);
;                   RT_VRD(va, 6); RT_VMM(vc, 5); __builtin_amdgcn_sched_barrier(0);
;                   RT_VRD(vc, 7); RT_VMM(va, 6); __builtin_amdgcn_sched_barrier(0);
;                   RT_VMM(vc, 7); __builtin_amdgcn_sched_barrier(0);
.LBB0_387:
	s_nop 6
	v_lshlrev_b32_e32 v98, 4, v0
	v_add_u32_e32 v99, s83, v98
	ds_write_b128 v99, v[190:193]
	ds_write_b128 v99, v[194:197] offset:1024
	s_lshl_b32 s12, s80, 6
	s_sub_i32 s12, 0x800, s12
	s_add_i32 s12, s12, s82
	v_add_u32_e32 v202, s12, v98
	ds_read_b128 v[242:245], v246 offset:4096
	ds_read_b128 v[106:109], v247 offset:4096
	s_waitcnt lgkmcnt(5)
	v_mfma_f32_32x32x16_bf16 v[82:97], v[234:237], v[190:193], v[82:97]
	s_waitcnt lgkmcnt(4)
	v_mfma_f32_32x32x16_bf16 v[82:97], v[238:241], v[194:197], v[82:97]
	ds_read_b128 v[234:237], v246 offset:8192
	ds_read_b128 v[238:241], v247 offset:8192
	s_waitcnt lgkmcnt(3)
	v_mfma_f32_32x32x16_bf16 v[66:81], v[242:245], v[190:193], v[66:81]
	s_waitcnt lgkmcnt(2)
	v_mfma_f32_32x32x16_bf16 v[66:81], v[106:109], v[194:197], v[66:81]
	ds_read_b128 v[242:245], v246 offset:12288
	ds_read_b128 v[106:109], v247 offset:12288
	s_waitcnt lgkmcnt(3)
	v_mfma_f32_32x32x16_bf16 v[50:65], v[234:237], v[190:193], v[50:65]
	s_waitcnt lgkmcnt(2)
	v_mfma_f32_32x32x16_bf16 v[50:65], v[238:241], v[194:197], v[50:65]
	ds_read_b128 v[234:237], v248
	ds_read_b128 v[238:241], v249
	s_barrier
	ds_read_b128 v[98:101], v202
	ds_read_b128 v[102:105], v202 offset:1024
	s_add_i32 s12, s30, 0x80
	s_cmp_eq_u32 s12, s11
	s_cbranch_scc1 .Lrk_skip
	s_add_i32 s13, s22, s6
	s_mov_b32 m0, s13
	s_add_i32 s12, s27, 0x10000
	buffer_load_dwordx4 v224, s[40:43], s12 offen lds
	s_add_i32 m0, s13, 0x2000
	s_add_i32 s12, s27, 0x20000
	buffer_load_dwordx4 v224, s[40:43], s12 offen lds
	s_add_i32 m0, s13, 0x4000
	s_add_i32 s12, s27, 0x30000
	buffer_load_dwordx4 v224, s[40:43], s12 offen lds
	s_add_i32 m0, s13, 0x6000
	s_add_i32 s12, s27, 0x40000
	buffer_load_dwordx4 v224, s[40:43], s12 offen lds
